# down-projection GEMM residual epilogues (P8, P10) de-serialized the same way as P5: 4 batches of 8 in-flight residual loads instead of 32 serialized load-wait-add-store steps per unit
# speedup vs baseline: 1.0218x; 1.0025x over previous
;     __device__ __forceinline__ void operator()(const f32x4 (&acc)[2][2][4][2], const Unit& u, int wr, int wc, int fr, int fq) const {
;         const int row0 = u.pm * BM + wr * 64 + fr; const int col0 = u.pn * BM + wc * 32 + 4 * fq;
;         const float* base = (u.pm * BM < split_row) ? base0 : base1;
; #pragma unroll
;         for (int ai = 0; ai < 2; ++ai)
; #pragma unroll
;             for (int m = 0; m < 4; ++m) { const size_t off = (size_t)(row0 + ai * HALF + m * 16) * ldc + col0;
; #pragma unroll
;                 for (int bj = 0; bj < 2; ++bj)
; #pragma unroll
;                     for (int n = 0; n < 2; ++n) { const f32x4 bs = *(const f32x4*)(base + off + bj * HALF + n * 16); *(f32x4*)(out + off + bj * HALF + n * 16) = bs + acc[ai][bj][m][n]; }
;                 if (m & 1) asm volatile("" ::: "memory"); }
.LBB0_786:
	v_lshl_add_u32 v140, s0, 8, v142
	v_lshl_or_b32 v136, s90, 8, v145
	v_ashrrev_i32_e32 v141, 31, v140
	v_ashrrev_i32_e32 v137, 31, v136
	v_lshlrev_b32_e32 v208, 13, v140
	v_lshl_add_u32 v208, v136, 2, v208
	v_add_u32_e32 v209, 0x20000, v208
	v_add_u32_e32 v210, 0x40000, v208
	v_add_u32_e32 v211, 0x60000, v208
	v_add_u32_e32 v212, 0x100000, v208
	v_add_u32_e32 v213, 0x120000, v208
	v_add_u32_e32 v214, 0x140000, v208
	v_add_u32_e32 v215, 0x160000, v208
	global_load_dwordx4 v[148:151], v208, s[94:95]
	global_load_dwordx4 v[152:155], v208, s[94:95] offset:64
	global_load_dwordx4 v[156:159], v208, s[94:95] offset:512
	global_load_dwordx4 v[160:163], v208, s[94:95] offset:576
	global_load_dwordx4 v[164:167], v209, s[94:95]
	global_load_dwordx4 v[168:171], v209, s[94:95] offset:64
	global_load_dwordx4 v[172:175], v209, s[94:95] offset:512
	global_load_dwordx4 v[176:179], v209, s[94:95] offset:576
	global_load_dwordx4 v[180:183], v210, s[94:95]
	global_load_dwordx4 v[184:187], v210, s[94:95] offset:64
	global_load_dwordx4 v[188:191], v210, s[94:95] offset:512
	global_load_dwordx4 v[192:195], v210, s[94:95] offset:576
	global_load_dwordx4 v[196:199], v211, s[94:95]
	global_load_dwordx4 v[200:203], v211, s[94:95] offset:64
	global_load_dwordx4 v[204:207], v211, s[94:95] offset:512
	global_load_dwordx4 v[136:139], v211, s[94:95] offset:576
	s_waitcnt vmcnt(8)
	v_pk_add_f32 v[124:125], v[124:125], v[148:149]
	v_pk_add_f32 v[126:127], v[126:127], v[150:151]
	global_store_dwordx4 v208, v[124:127], s[94:95]
	v_pk_add_f32 v[120:121], v[120:121], v[152:153]
	v_pk_add_f32 v[122:123], v[122:123], v[154:155]
	global_store_dwordx4 v208, v[120:123], s[94:95] offset:64
	v_pk_add_f32 v[116:117], v[116:117], v[156:157]
	v_pk_add_f32 v[118:119], v[118:119], v[158:159]
	global_store_dwordx4 v208, v[116:119], s[94:95] offset:512
	v_pk_add_f32 v[112:113], v[112:113], v[160:161]
	v_pk_add_f32 v[114:115], v[114:115], v[162:163]
	global_store_dwordx4 v208, v[112:115], s[94:95] offset:576
	v_pk_add_f32 v[108:109], v[108:109], v[164:165]
	v_pk_add_f32 v[110:111], v[110:111], v[166:167]
	global_store_dwordx4 v209, v[108:111], s[94:95]
	v_pk_add_f32 v[104:105], v[104:105], v[168:169]
	v_pk_add_f32 v[106:107], v[106:107], v[170:171]
	global_store_dwordx4 v209, v[104:107], s[94:95] offset:64
	v_pk_add_f32 v[100:101], v[100:101], v[172:173]
	v_pk_add_f32 v[102:103], v[102:103], v[174:175]
	global_store_dwordx4 v209, v[100:103], s[94:95] offset:512
	v_pk_add_f32 v[96:97], v[96:97], v[176:177]
	v_pk_add_f32 v[98:99], v[98:99], v[178:179]
	global_store_dwordx4 v209, v[96:99], s[94:95] offset:576
	global_load_dwordx4 v[148:151], v212, s[94:95]
	global_load_dwordx4 v[152:155], v212, s[94:95] offset:64
	global_load_dwordx4 v[156:159], v212, s[94:95] offset:512
	global_load_dwordx4 v[160:163], v212, s[94:95] offset:576
	global_load_dwordx4 v[164:167], v213, s[94:95]
	global_load_dwordx4 v[168:171], v213, s[94:95] offset:64
	global_load_dwordx4 v[172:175], v213, s[94:95] offset:512
	global_load_dwordx4 v[176:179], v213, s[94:95] offset:576
	s_waitcnt vmcnt(8)
;     __device__ __forceinline__ void operator()(const f32x4 (&acc)[2][2][4][2], const Unit& u, int wr, int wc, int fr, int fq) const {
;         const int row0 = u.pm * BM + wr * 64 + fr; const int col0 = u.pn * BM + wc * 32 + 4 * fq;
;         const float* base = (u.pm * BM < split_row) ? base0 : base1;
; #pragma unroll
;         for (int ai = 0; ai < 2; ++ai)
; #pragma unroll
;             for (int m = 0; m < 4; ++m) { const size_t off = (size_t)(row0 + ai * HALF + m * 16) * ldc + col0;
; #pragma unroll
;                 for (int bj = 0; bj < 2; ++bj)
; #pragma unroll
;                     for (int n = 0; n < 2; ++n) { const f32x4 bs = *(const f32x4*)(base + off + bj * HALF + n * 16); *(f32x4*)(out + off + bj * HALF + n * 16) = bs + acc[ai][bj][m][n]; }
;                 if (m & 1) asm volatile("" ::: "memory"); }
	v_pk_add_f32 v[92:93], v[92:93], v[180:181]
	v_pk_add_f32 v[94:95], v[94:95], v[182:183]
	global_store_dwordx4 v210, v[92:95], s[94:95]
	v_pk_add_f32 v[88:89], v[88:89], v[184:185]
	v_pk_add_f32 v[90:91], v[90:91], v[186:187]
	global_store_dwordx4 v210, v[88:91], s[94:95] offset:64
	v_pk_add_f32 v[84:85], v[84:85], v[188:189]
	v_pk_add_f32 v[86:87], v[86:87], v[190:191]
	global_store_dwordx4 v210, v[84:87], s[94:95] offset:512
	v_pk_add_f32 v[80:81], v[80:81], v[192:193]
	v_pk_add_f32 v[82:83], v[82:83], v[194:195]
	global_store_dwordx4 v210, v[80:83], s[94:95] offset:576
	v_pk_add_f32 v[76:77], v[76:77], v[196:197]
	v_pk_add_f32 v[78:79], v[78:79], v[198:199]
	global_store_dwordx4 v211, v[76:79], s[94:95]
	v_pk_add_f32 v[72:73], v[72:73], v[200:201]
	v_pk_add_f32 v[74:75], v[74:75], v[202:203]
	global_store_dwordx4 v211, v[72:75], s[94:95] offset:64
	v_pk_add_f32 v[68:69], v[68:69], v[204:205]
	v_pk_add_f32 v[70:71], v[70:71], v[206:207]
	global_store_dwordx4 v211, v[68:71], s[94:95] offset:512
	v_pk_add_f32 v[64:65], v[64:65], v[136:137]
	v_pk_add_f32 v[66:67], v[66:67], v[138:139]
	global_store_dwordx4 v211, v[64:67], s[94:95] offset:576
	global_load_dwordx4 v[180:183], v214, s[94:95]
	global_load_dwordx4 v[184:187], v214, s[94:95] offset:64
	global_load_dwordx4 v[188:191], v214, s[94:95] offset:512
	global_load_dwordx4 v[192:195], v214, s[94:95] offset:576
	global_load_dwordx4 v[196:199], v215, s[94:95]
	global_load_dwordx4 v[200:203], v215, s[94:95] offset:64
	global_load_dwordx4 v[204:207], v215, s[94:95] offset:512
	global_load_dwordx4 v[136:139], v215, s[94:95] offset:576
	s_waitcnt vmcnt(8)
	v_pk_add_f32 v[60:61], v[60:61], v[148:149]
	v_pk_add_f32 v[62:63], v[62:63], v[150:151]
	global_store_dwordx4 v212, v[60:63], s[94:95]
	v_pk_add_f32 v[56:57], v[56:57], v[152:153]
	v_pk_add_f32 v[58:59], v[58:59], v[154:155]
	global_store_dwordx4 v212, v[56:59], s[94:95] offset:64
	v_pk_add_f32 v[52:53], v[52:53], v[156:157]
	v_pk_add_f32 v[54:55], v[54:55], v[158:159]
	global_store_dwordx4 v212, v[52:55], s[94:95] offset:512
	v_pk_add_f32 v[48:49], v[48:49], v[160:161]
	v_pk_add_f32 v[50:51], v[50:51], v[162:163]
	global_store_dwordx4 v212, v[48:51], s[94:95] offset:576
	v_pk_add_f32 v[44:45], v[44:45], v[164:165]
	v_pk_add_f32 v[46:47], v[46:47], v[166:167]
	global_store_dwordx4 v213, v[44:47], s[94:95]
	v_pk_add_f32 v[40:41], v[40:41], v[168:169]
	v_pk_add_f32 v[42:43], v[42:43], v[170:171]
	global_store_dwordx4 v213, v[40:43], s[94:95] offset:64
	v_pk_add_f32 v[36:37], v[36:37], v[172:173]
	v_pk_add_f32 v[38:39], v[38:39], v[174:175]
	global_store_dwordx4 v213, v[36:39], s[94:95] offset:512
	v_pk_add_f32 v[32:33], v[32:33], v[176:177]
	v_pk_add_f32 v[34:35], v[34:35], v[178:179]
	global_store_dwordx4 v213, v[32:35], s[94:95] offset:576
	s_waitcnt vmcnt(0)
	v_pk_add_f32 v[28:29], v[28:29], v[180:181]
	v_pk_add_f32 v[30:31], v[30:31], v[182:183]
	global_store_dwordx4 v214, v[28:31], s[94:95]
	v_pk_add_f32 v[24:25], v[24:25], v[184:185]
	v_pk_add_f32 v[26:27], v[26:27], v[186:187]
	global_store_dwordx4 v214, v[24:27], s[94:95] offset:64
	v_pk_add_f32 v[20:21], v[20:21], v[188:189]
	v_pk_add_f32 v[22:23], v[22:23], v[190:191]
	global_store_dwordx4 v214, v[20:23], s[94:95] offset:512
	v_pk_add_f32 v[16:17], v[16:17], v[192:193]
	v_pk_add_f32 v[18:19], v[18:19], v[194:195]
	global_store_dwordx4 v214, v[16:19], s[94:95] offset:576
	v_pk_add_f32 v[12:13], v[12:13], v[196:197]
	v_pk_add_f32 v[14:15], v[14:15], v[198:199]
	global_store_dwordx4 v215, v[12:15], s[94:95]
	v_pk_add_f32 v[8:9], v[8:9], v[200:201]
	v_pk_add_f32 v[10:11], v[10:11], v[202:203]
	global_store_dwordx4 v215, v[8:11], s[94:95] offset:64
	v_pk_add_f32 v[4:5], v[4:5], v[204:205]
	v_pk_add_f32 v[6:7], v[6:7], v[206:207]
	global_store_dwordx4 v215, v[4:7], s[94:95] offset:512
	v_pk_add_f32 v[0:1], v[0:1], v[136:137]
	v_pk_add_f32 v[2:3], v[2:3], v[138:139]
	global_store_dwordx4 v215, v[0:3], s[94:95] offset:576
	s_mov_b64 s[0:1], -1
	s_andn2_b64 vcc, exec, s[36:37]
	s_cbranch_vccnz .LBB0_775
	s_andn2_b64 vcc, exec, s[92:93]
	s_cbranch_vccnz .LBB0_774
	s_barrier
	s_branch .LBB0_774
